# sgu unit: mixing-weight and s_v row loads issued before the LayerNorm statistics block so a single wait covers both load groups
# baseline (speedup 1.0000x reference)
.LBB0_444:
	s_bfe_u32 s30, s25, 0x10008
	s_lshl_b32 s38, s30, 6
	s_bfe_u32 s39, s25, 0x60002
	s_or_b32 s56, s38, s39
	s_and_b32 s38, s25, 3
	s_xor_b32 s39, s38, 3
	s_cmp_eq_u32 s30, 0
	s_cselect_b32 s55, s38, s39
	s_cmpk_gt_i32 s25, 0x1ff
	s_mov_b64 s[38:39], -1
	s_cbranch_scc0 .LBB0_448
	s_load_dwordx2 s[38:39], s[26:27], 0x78
	s_lshl_b64 s[44:45], s[40:41], 2
	v_mov_b32_e32 v34, v224
	s_waitcnt lgkmcnt(0)
	v_mov_b64_e32 v[4:5], s[28:29]
	v_readfirstlane_b32 s30, v34
	s_add_u32 s38, s38, s44
	s_addc_u32 s39, s39, s45
	s_ashr_i32 s60, s30, 6
	s_ashr_i32 s30, s30, 2
	v_and_b32_e32 v71, 15, v34
	s_lshl_b32 s46, s60, 5
	v_lshrrev_b32_e32 v2, 2, v34
	s_andn2_b32 s30, s30, 63
	s_and_b32 s57, s46, 0x60
	v_and_b32_e32 v0, 16, v34
	v_and_b32_e32 v2, 8, v2
	v_or_b32_e32 v75, s30, v71
	s_lshl_b32 s61, s55, 7
	v_or3_b32 v0, v2, v0, s57
	s_lshl_b32 s62, s56, 7
	v_add_u32_e32 v2, s61, v75
	v_ashrrev_i32_e32 v3, 31, v2
	v_add_u32_e32 v14, s62, v75
	v_lshl_add_u64 v[2:3], v[2:3], 2, s[38:39]
	v_mad_i64_i32 v[6:7], s[38:39], v14, s23, v[4:5]
	s_lshl_b32 s30, s55, 8
	v_lshl_add_u64 v[6:7], v[6:7], 0, s[30:31]
	v_lshlrev_b32_e32 v0, 1, v0
	v_lshl_add_u64 v[66:67], v[6:7], 0, v[0:1]
	v_mov_b64_e32 v[6:7], s[50:51]
	v_or_b32_e32 v69, 16, v14
	v_mad_i64_i32 v[8:9], s[38:39], v14, s21, v[6:7]
	v_mad_i64_i32 v[10:11], s[38:39], v69, s23, v[4:5]
	v_lshl_add_u64 v[8:9], v[8:9], 0, s[30:31]
	v_lshl_add_u64 v[10:11], v[10:11], 0, s[30:31]
	v_lshl_add_u64 v[8:9], v[8:9], 0, v[0:1]
	v_lshl_add_u64 v[10:11], v[10:11], 0, v[0:1]
	v_or_b32_e32 v65, 32, v14
	global_load_dwordx4 v[26:29], v[66:67], off offset:2048
	global_load_dwordx4 v[30:33], v[8:9], off offset:3072
	global_load_dwordx4 v[18:21], v[10:11], off offset:2048
	v_mad_i64_i32 v[8:9], s[38:39], v69, s21, v[6:7]
	v_mad_i64_i32 v[10:11], s[38:39], v65, s23, v[4:5]
	v_lshl_add_u64 v[8:9], v[8:9], 0, s[30:31]
	v_lshl_add_u64 v[10:11], v[10:11], 0, s[30:31]
	v_lshl_add_u64 v[8:9], v[8:9], 0, v[0:1]
	v_lshl_add_u64 v[10:11], v[10:11], 0, v[0:1]
	v_or_b32_e32 v63, 48, v14
	global_load_dwordx4 v[22:25], v[8:9], off offset:3072
	s_nop 0
	global_load_dwordx4 v[10:13], v[10:11], off offset:2048
	v_mad_i64_i32 v[8:9], s[38:39], v65, s21, v[6:7]
	global_load_dword v70, v[2:3], off
	global_load_dword v68, v[2:3], off offset:64
	global_load_dword v64, v[2:3], off offset:128
	global_load_dword v62, v[2:3], off offset:192
	v_mad_i64_i32 v[2:3], s[38:39], v63, s23, v[4:5]
	v_mad_i64_i32 v[6:7], s[38:39], v63, s21, v[6:7]
	v_lshl_add_u64 v[8:9], v[8:9], 0, s[30:31]
	v_lshl_add_u64 v[2:3], v[2:3], 0, s[30:31]
	v_lshl_add_u64 v[6:7], v[6:7], 0, s[30:31]
	v_lshl_add_u64 v[8:9], v[8:9], 0, v[0:1]
	v_lshl_add_u64 v[2:3], v[2:3], 0, v[0:1]
	v_lshl_add_u64 v[6:7], v[6:7], 0, v[0:1]
	global_load_dwordx4 v[14:17], v[8:9], off offset:3072
	s_nop 0
	global_load_dwordx4 v[2:5], v[2:3], off offset:2048
	s_movk_i32 s30, 0x80
	global_load_dwordx4 v[6:9], v[6:7], off offset:3072
	s_load_dwordx4 s[64:67], s[26:27], 0x60
	v_ashrrev_i32_e32 v35, 4, v34
	v_lshlrev_b32_e32 v36, 4, v71
	v_mov_b32_e32 v37, v1
	v_lshlrev_b32_e32 v40, 7, v35
	s_waitcnt lgkmcnt(0)
	s_add_u32 s47, s64, s44
	s_addc_u32 s46, s65, s45
	s_add_u32 s38, s66, s44
	s_addc_u32 s39, s67, s45
	s_lshl_b32 s30, s55, 15
	s_add_u32 s44, s13, s30
	s_addc_u32 s45, s16, 0
	v_lshl_add_u64 v[38:39], s[44:45], 0, v[36:37]
	v_ashrrev_i32_e32 v41, 31, v40
	v_add_u32_e32 v37, 0x200, v34
	v_lshl_add_u64 v[40:41], v[40:41], 1, v[38:39]
	v_ashrrev_i32_e32 v37, 4, v37
	global_load_dwordx4 v[50:53], v[40:41], off
	v_lshlrev_b32_e32 v40, 7, v37
	v_ashrrev_i32_e32 v41, 31, v40
	v_lshl_add_u64 v[40:41], v[40:41], 1, v[38:39]
	global_load_dwordx4 v[54:57], v[40:41], off
	v_add_u32_e32 v40, 0x400, v34
	v_ashrrev_i32_e32 v74, 4, v40
	v_lshlrev_b32_e32 v40, 7, v74
	v_ashrrev_i32_e32 v41, 31, v40
	v_lshl_add_u64 v[40:41], v[40:41], 1, v[38:39]
	global_load_dwordx4 v[58:61], v[40:41], off
	v_add_u32_e32 v40, 0x600, v34
	v_ashrrev_i32_e32 v77, 4, v40
	v_lshlrev_b32_e32 v40, 7, v77
	v_ashrrev_i32_e32 v41, 31, v40
	v_lshl_add_u64 v[38:39], v[40:41], 1, v[38:39]
	global_load_dwordx4 v[78:81], v[38:39], off
	s_lshl_b32 s44, s60, 4
	v_lshrrev_b32_e32 v38, 4, v34
	v_and_or_b32 v95, s44, 48, v71
	v_bfi_b32 v94, -4, s60, v38
	v_lshl_or_b32 v38, v95, 1, s62
	v_mul_u32_u24_e32 v38, 0xa00, v38
	v_mov_b32_e32 v39, v1
	v_lshlrev_b32_e32 v38, 1, v38
	s_lshl_b32 s30, s61, 1
	v_lshl_add_u64 v[38:39], s[50:51], 0, v[38:39]
	v_lshl_add_u64 v[38:39], v[38:39], 0, s[30:31]
	s_mov_b64 s[44:45], 0x1000
	v_bfe_u32 v76, v34, 4, 2
	v_add_u32_e32 v34, 0, v36
	v_lshl_add_u64 v[38:39], v[38:39], 0, s[44:45]
	v_mad_u64_u32 v[72:73], s[44:45], v35, s90, v[34:35]
	v_mad_u64_u32 v[82:83], s[44:45], v37, s90, v[34:35]
	v_mad_u64_u32 v[84:85], s[44:45], v74, s90, v[34:35]
	v_mad_u64_u32 v[86:87], s[44:45], v77, s90, v[34:35]
	v_lshlrev_b32_e32 v40, 3, v94
	s_and_b32 s44, s60, -4
	v_ashrrev_i32_e32 v41, 31, v40
	s_lshl_b32 s60, s61, 2
	s_add_i32 s44, s44, 8
	v_lshl_add_u64 v[42:43], v[40:41], 1, v[38:39]
	s_movk_i32 s62, 0x1000
	v_or_b32_e32 v96, s44, v76
	s_add_u32 s44, s47, s60
	v_add_co_u32_e32 v36, vcc, s62, v42
	s_addc_u32 s45, s46, 0
	global_load_dwordx4 v[46:49], v[42:43], off
	v_addc_co_u32_e32 v37, vcc, 0, v43, vcc
	v_lshlrev_b32_e32 v88, 3, v96
	s_add_u32 s38, s38, s60
	global_load_dwordx4 v[42:45], v[36:37], off offset:1024
	v_lshlrev_b64 v[34:35], 2, v[40:41]
	v_ashrrev_i32_e32 v89, 31, v88
	s_addc_u32 s39, s39, 0
	v_lshl_add_u64 v[90:91], s[44:45], 0, v[34:35]
	v_lshl_add_u64 v[92:93], s[38:39], 0, v[34:35]
	v_lshl_add_u64 v[34:35], v[88:89], 1, v[38:39]
	global_load_dwordx4 v[38:41], v[34:35], off
	v_add_co_u32_e32 v34, vcc, s62, v34
	v_lshl_add_u32 v74, v95, 2, 0
	s_nop 0
	v_addc_co_u32_e32 v35, vcc, 0, v35, vcc
	global_load_dwordx4 v[34:37], v[34:35], off offset:1024
	s_movk_i32 s60, 0x880
	s_movk_i32 s91, 0x1000
	v_readfirstlane_b32 s64, v224
	s_cmpk_gt_i32 s64, 0x7f
	s_cbranch_scc1 .LBB0_447
	s_lshl_b32 s66, s56, 7
	v_add_u32_e32 v166, s66, v224
	v_ashrrev_i32_e32 v167, 31, v166
	v_lshlrev_b64 v[166:167], 6, v[166:167]
	v_lshl_add_u64 v[178:179], s[42:43], 0, v[166:167]
	global_load_dwordx4 v[166:169], v[178:179], off
	global_load_dwordx4 v[170:173], v[178:179], off offset:16
	global_load_dwordx4 v[174:177], v[178:179], off offset:32
	s_nop 0
	global_load_dwordx4 v[178:181], v[178:179], off offset:48
	s_mov_b32 s66, 0x3b000000
	s_waitcnt vmcnt(3)
	v_pk_add_f32 v[166:167], v[166:167], v[168:169]
	s_waitcnt vmcnt(2)
	v_pk_add_f32 v[168:169], v[170:171], v[172:173]
	s_waitcnt vmcnt(1)
	v_pk_add_f32 v[170:171], v[174:175], v[176:177]
	v_pk_add_f32 v[166:167], v[166:167], v[168:169]
	s_waitcnt vmcnt(0)
	v_pk_add_f32 v[172:173], v[178:179], v[180:181]
	v_pk_add_f32 v[166:167], v[166:167], v[170:171]
	s_nop 0
	v_pk_add_f32 v[166:167], v[166:167], v[172:173]
	s_nop 0
	v_pk_mul_f32 v[166:167], v[166:167], s[66:67] op_sel_hi:[1,0]
	s_nop 0
	v_fma_f32 v165, -v166, v166, v167
	v_max_f32_e32 v165, 0, v165
	v_add_f32_e32 v165, 0x358637bd, v165
	v_mul_f32_e32 v167, 0x4f800000, v165
	v_cmp_gt_f32_e32 vcc, s7, v165
	s_nop 1
	v_cndmask_b32_e32 v165, v165, v167, vcc
	v_sqrt_f32_e32 v167, v165
	s_nop 0
	v_add_u32_e32 v168, -1, v167
	v_add_u32_e32 v169, 1, v167
	v_fma_f32 v170, -v168, v167, v165
	v_fma_f32 v171, -v169, v167, v165
	v_cmp_ge_f32_e64 s[64:65], 0, v170
	s_nop 1
	v_cndmask_b32_e64 v167, v167, v168, s[64:65]
	v_cmp_lt_f32_e64 s[64:65], 0, v171
	s_nop 1
	v_cndmask_b32_e64 v167, v167, v169, s[64:65]
	v_mul_f32_e32 v168, 0x37800000, v167
	v_cndmask_b32_e32 v167, v167, v168, vcc
	v_cmp_class_f32_e32 vcc, v165, v228
	v_lshl_add_u32 v169, v224, 3, 0
	s_nop 0
	v_cndmask_b32_e32 v165, v167, v165, vcc
	v_div_scale_f32 v167, s[64:65], v165, v165, 1.0
	v_rcp_f32_e32 v168, v167
	v_div_scale_f32 v170, vcc, 1.0, v165, 1.0
	v_fma_f32 v171, -v167, v168, 1.0
	v_fmac_f32_e32 v168, v171, v168
	v_mul_f32_e32 v171, v170, v168
	v_fma_f32 v172, -v167, v171, v170
	v_fmac_f32_e32 v171, v172, v168
	v_fma_f32 v167, -v167, v171, v170
	v_div_fmas_f32 v167, v167, v168, v171
	v_div_fixup_f32 v167, v167, v165, 1.0
	v_add_u32_e32 v165, 0x11000, v169
	ds_write_b64 v165, v[166:167]
.LBB0_447:
	s_waitcnt vmcnt(7)
	ds_write_b128 v72, v[50:53]
	s_waitcnt vmcnt(6)
	ds_write_b128 v82, v[54:57]
	s_waitcnt vmcnt(5)
	ds_write_b128 v84, v[58:61]
	s_waitcnt vmcnt(4)
	ds_write_b128 v86, v[78:81]
	s_waitcnt lgkmcnt(0)
	s_barrier
	global_load_dwordx4 v[54:57], v[90:91], off
	global_load_dwordx4 v[58:61], v[92:93], off
	global_load_dwordx4 v[78:81], v[90:91], off offset:16
	global_load_dwordx4 v[50:53], v[92:93], off offset:16
	v_lshl_add_u32 v72, v95, 4, 0
	v_add_u32_e32 v77, 0x11000, v72
	ds_read_b128 v[82:85], v77
	v_mad_u64_u32 v[72:73], s[46:47], v94, s60, v[74:75]
	v_lshlrev_b64 v[86:87], 2, v[88:89]
	s_waitcnt vmcnt(7)
	v_lshlrev_b32_e32 v73, 16, v46
	v_and_b32_e32 v46, 0xffff0000, v46
	v_lshlrev_b32_e32 v88, 16, v47
	v_and_b32_e32 v47, 0xffff0000, v47
	v_lshlrev_b32_e32 v89, 16, v48
	v_and_b32_e32 v48, 0xffff0000, v48
	v_lshlrev_b32_e32 v90, 16, v49
	v_and_b32_e32 v49, 0xffff0000, v49
	s_waitcnt lgkmcnt(0)
	v_sub_f32_e32 v73, v73, v82
	v_sub_f32_e32 v46, v46, v82
	v_sub_f32_e32 v88, v88, v82
	v_sub_f32_e32 v47, v47, v82
	v_sub_f32_e32 v89, v89, v82
	v_sub_f32_e32 v48, v48, v82
	v_sub_f32_e32 v90, v90, v82
	v_sub_f32_e32 v49, v49, v82
	s_waitcnt vmcnt(6)
	v_lshlrev_b32_e32 v82, 16, v42
	v_and_b32_e32 v42, 0xffff0000, v42
	v_lshlrev_b32_e32 v93, 16, v45
	v_and_b32_e32 v45, 0xffff0000, v45
	v_sub_f32_e32 v42, v42, v84
	v_lshlrev_b32_e32 v91, 16, v43
	v_sub_f32_e32 v82, v82, v84
	v_sub_f32_e32 v45, v45, v84
	v_mul_f32_e32 v42, v85, v42
	v_and_b32_e32 v43, 0xffff0000, v43
	v_mul_f32_e32 v73, v83, v73
	v_mul_f32_e32 v46, v83, v46
	v_mul_f32_e32 v88, v83, v88
	v_mul_f32_e32 v47, v83, v47
	v_mul_f32_e32 v89, v83, v89
	v_mul_f32_e32 v48, v83, v48
	v_mul_f32_e32 v90, v83, v90
	v_mul_f32_e32 v49, v83, v49
	v_sub_f32_e32 v83, v91, v84
	v_mul_f32_e32 v82, v85, v82
	v_mul_f32_e32 v45, v85, v45
	v_lshlrev_b32_e32 v92, 16, v44
	v_sub_f32_e32 v43, v43, v84
	v_mul_f32_e32 v83, v85, v83
	v_and_b32_e32 v44, 0xffff0000, v44
	v_sub_f32_e32 v91, v92, v84
	v_mul_f32_e32 v43, v85, v43
	s_waitcnt vmcnt(2)
	v_fma_f32 v42, v55, v42, v59
	v_fma_f32 v73, v54, v73, v58
	v_fma_f32 v54, v54, v82, v58
	v_fma_f32 v46, v55, v46, v59
	s_waitcnt vmcnt(0)
	v_fma_f32 v49, v49, v81, v53
	v_fmac_f32_e32 v53, v81, v45
	v_cvt_pk_bf16_f32 v45, v73, v54
	ds_write_b32 v72, v45 offset:34816
	v_cvt_pk_bf16_f32 v42, v46, v42
	v_fma_f32 v55, v56, v88, v60
	v_fma_f32 v56, v56, v83, v60
	ds_write_b32 v72, v42 offset:35088
	v_cvt_pk_bf16_f32 v42, v55, v56
	v_sub_f32_e32 v44, v44, v84
	v_sub_f32_e32 v92, v93, v84
	v_mul_f32_e32 v84, v85, v91
	v_fma_f32 v47, v57, v47, v61
	v_fmac_f32_e32 v61, v57, v43
	ds_write_b32 v72, v42 offset:35360
	v_cvt_pk_bf16_f32 v42, v47, v61
	v_mul_f32_e32 v44, v85, v44
	v_fma_f32 v43, v89, v78, v50
	v_fma_f32 v50, v78, v84, v50
	ds_write_b32 v72, v42 offset:35632
	v_cvt_pk_bf16_f32 v42, v43, v50
	v_mul_f32_e32 v91, v85, v92
	v_fma_f32 v48, v48, v79, v51
	v_fma_f32 v44, v79, v44, v51
	ds_write_b32 v72, v42 offset:35904
	v_cvt_pk_bf16_f32 v42, v48, v44
	v_fma_f32 v51, v90, v80, v52
	v_fma_f32 v52, v80, v91, v52
	ds_write_b32 v72, v42 offset:36176
	v_cvt_pk_bf16_f32 v42, v51, v52
	ds_write_b32 v72, v42 offset:36448
	v_lshl_add_u64 v[42:43], s[44:45], 0, v[86:87]
	v_cvt_pk_bf16_f32 v60, v49, v53
	global_load_dwordx4 v[54:57], v[42:43], off
	v_lshl_add_u64 v[44:45], s[38:39], 0, v[86:87]
	global_load_dwordx4 v[46:49], v[44:45], off
	global_load_dwordx4 v[50:53], v[42:43], off offset:16
	s_nop 0
	global_load_dwordx4 v[42:45], v[44:45], off offset:16
	v_mad_u64_u32 v[58:59], s[38:39], v96, s60, v[74:75]
	ds_write_b32 v72, v60 offset:36720
	v_lshlrev_b32_e32 v59, 16, v38
	v_and_b32_e32 v61, 0xffff0000, v38
	v_lshlrev_b32_e32 v73, 16, v39
	v_and_b32_e32 v74, 0xffff0000, v39
	v_lshlrev_b32_e32 v78, 16, v40
	v_and_b32_e32 v79, 0xffff0000, v40
	v_lshlrev_b32_e32 v80, 16, v41
	v_and_b32_e32 v81, 0xffff0000, v41
	ds_read_b128 v[38:41], v77
	v_lshlrev_b32_e32 v82, 16, v34
	v_and_b32_e32 v34, 0xffff0000, v34
	v_lshlrev_b32_e32 v72, 16, v37
	v_and_b32_e32 v37, 0xffff0000, v37
	s_waitcnt lgkmcnt(0)
	v_sub_f32_e32 v34, v34, v40
	v_lshlrev_b32_e32 v83, 16, v35
	v_and_b32_e32 v35, 0xffff0000, v35
	v_lshlrev_b32_e32 v60, 16, v36
	v_and_b32_e32 v36, 0xffff0000, v36
	v_sub_f32_e32 v59, v59, v38
	v_sub_f32_e32 v77, v82, v40
	v_sub_f32_e32 v61, v61, v38
	v_sub_f32_e32 v73, v73, v38
	v_sub_f32_e32 v74, v74, v38
	v_sub_f32_e32 v78, v78, v38
	v_sub_f32_e32 v79, v79, v38
	v_sub_f32_e32 v80, v80, v38
	v_sub_f32_e32 v38, v81, v38
	v_sub_f32_e32 v37, v37, v40
	v_mul_f32_e32 v34, v41, v34
	v_sub_f32_e32 v82, v83, v40
	v_sub_f32_e32 v35, v35, v40
	v_sub_f32_e32 v60, v60, v40
	v_sub_f32_e32 v36, v36, v40
	v_sub_f32_e32 v72, v72, v40
	v_mul_f32_e32 v40, v39, v59
	v_mul_f32_e32 v59, v41, v77
	v_mul_f32_e32 v61, v39, v61
	v_mul_f32_e32 v38, v39, v38
	v_mul_f32_e32 v37, v41, v37
	v_mul_f32_e32 v73, v39, v73
	v_mul_f32_e32 v77, v41, v82
	v_mul_f32_e32 v74, v39, v74
	v_mul_f32_e32 v35, v41, v35
	v_mul_f32_e32 v78, v39, v78
	v_mul_f32_e32 v60, v41, v60
	v_mul_f32_e32 v79, v39, v79
	v_mul_f32_e32 v36, v41, v36
	v_mul_f32_e32 v80, v39, v80
	v_mul_f32_e32 v72, v41, v72
	s_waitcnt vmcnt(2)
	v_fma_f32 v34, v55, v34, v47
	v_fma_f32 v39, v54, v40, v46
	v_fma_f32 v40, v54, v59, v46
	v_fma_f32 v41, v55, v61, v47
	s_waitcnt vmcnt(0)
	v_fma_f32 v38, v38, v53, v45
	v_fmac_f32_e32 v45, v53, v37
	v_cvt_pk_bf16_f32 v37, v39, v40
	ds_write_b32 v58, v37 offset:34816
	v_cvt_pk_bf16_f32 v34, v41, v34
	v_fma_f32 v46, v56, v73, v48
	v_fma_f32 v47, v56, v77, v48
	ds_write_b32 v58, v34 offset:35088
	v_cvt_pk_bf16_f32 v34, v46, v47
	v_fma_f32 v48, v57, v74, v49
	v_fmac_f32_e32 v49, v57, v35
	ds_write_b32 v58, v34 offset:35360
	v_cvt_pk_bf16_f32 v34, v48, v49
	v_fma_f32 v35, v78, v50, v42
	v_fma_f32 v42, v50, v60, v42
	ds_write_b32 v58, v34 offset:35632
	v_cvt_pk_bf16_f32 v34, v35, v42
	v_fma_f32 v50, v79, v51, v43
	v_fma_f32 v36, v51, v36, v43
	ds_write_b32 v58, v34 offset:35904
	v_cvt_pk_bf16_f32 v34, v50, v36
	v_fma_f32 v43, v80, v52, v44
	v_fma_f32 v44, v52, v72, v44
	ds_write_b32 v58, v34 offset:36176
	v_cvt_pk_bf16_f32 v34, v43, v44
	ds_write_b32 v58, v34 offset:36448
	v_cvt_pk_bf16_f32 v34, v38, v45
	ds_write_b32 v58, v34 offset:36720
	v_or_b32_e32 v34, s57, v71
	v_lshl_add_u32 v38, v76, 4, 0
	v_mad_u32_u24 v71, v34, s90, v38
	s_waitcnt lgkmcnt(0)
	s_barrier
	ds_read_b128 v[34:37], v71 offset:34816
	ds_read_b128 v[46:49], v71 offset:39168
	v_mad_u64_u32 v[88:89], s[38:39], v75, s90, v[38:39]
	ds_read_b128 v[38:41], v88
	ds_read_b128 v[50:53], v88 offset:4352
	ds_read_b128 v[58:61], v88 offset:8704
	ds_read_b128 v[76:79], v88 offset:13056
	ds_read_b128 v[80:83], v71 offset:34880
	ds_read_b128 v[84:87], v71 offset:39232
	s_waitcnt lgkmcnt(5)
	v_mfma_f32_16x16x32_bf16 v[42:45], v[34:37], v[38:41], 0
	v_mfma_f32_16x16x32_bf16 v[38:41], v[46:49], v[38:41], 0
	s_waitcnt lgkmcnt(4)
	v_mfma_f32_16x16x32_bf16 v[54:57], v[34:37], v[50:53], 0
	v_mfma_f32_16x16x32_bf16 v[50:53], v[46:49], v[50:53], 0
	s_waitcnt lgkmcnt(3)
	v_mfma_f32_16x16x32_bf16 v[72:75], v[34:37], v[58:61], 0
	v_mfma_f32_16x16x32_bf16 v[58:61], v[46:49], v[58:61], 0
	s_waitcnt lgkmcnt(2)
	v_mfma_f32_16x16x32_bf16 v[34:37], v[34:37], v[76:79], 0
	v_mfma_f32_16x16x32_bf16 v[46:49], v[46:49], v[76:79], 0
	ds_read_b128 v[76:79], v88 offset:64
	s_waitcnt lgkmcnt(0)
	v_mfma_f32_16x16x32_bf16 v[42:45], v[80:83], v[76:79], v[42:45]
	v_mfma_f32_16x16x32_bf16 v[38:41], v[84:87], v[76:79], v[38:41]
	ds_read_b128 v[76:79], v88 offset:4416
	s_waitcnt lgkmcnt(0)
	v_mfma_f32_16x16x32_bf16 v[54:57], v[80:83], v[76:79], v[54:57]
	v_mfma_f32_16x16x32_bf16 v[50:53], v[84:87], v[76:79], v[50:53]
	ds_read_b128 v[76:79], v88 offset:8768
	s_waitcnt lgkmcnt(0)
	v_mfma_f32_16x16x32_bf16 v[72:75], v[80:83], v[76:79], v[72:75]
	v_mfma_f32_16x16x32_bf16 v[58:61], v[84:87], v[76:79], v[58:61]
	ds_read_b128 v[76:79], v88 offset:13120
	s_waitcnt lgkmcnt(0)
	v_mfma_f32_16x16x32_bf16 v[34:37], v[80:83], v[76:79], v[34:37]
	ds_read_b128 v[80:83], v71 offset:34944
	v_mfma_f32_16x16x32_bf16 v[46:49], v[84:87], v[76:79], v[46:49]
	ds_read_b128 v[84:87], v71 offset:39296
	ds_read_b128 v[76:79], v88 offset:128
	s_waitcnt lgkmcnt(0)
	v_mfma_f32_16x16x32_bf16 v[42:45], v[80:83], v[76:79], v[42:45]
	v_mfma_f32_16x16x32_bf16 v[38:41], v[84:87], v[76:79], v[38:41]
	ds_read_b128 v[76:79], v88 offset:4480
	s_waitcnt lgkmcnt(0)
	v_mfma_f32_16x16x32_bf16 v[54:57], v[80:83], v[76:79], v[54:57]
	v_mfma_f32_16x16x32_bf16 v[50:53], v[84:87], v[76:79], v[50:53]
	ds_read_b128 v[76:79], v88 offset:8832
	s_waitcnt lgkmcnt(0)
	v_mfma_f32_16x16x32_bf16 v[72:75], v[80:83], v[76:79], v[72:75]
	v_mfma_f32_16x16x32_bf16 v[58:61], v[84:87], v[76:79], v[58:61]
	ds_read_b128 v[76:79], v88 offset:13184
	s_waitcnt lgkmcnt(0)
	v_mfma_f32_16x16x32_bf16 v[34:37], v[80:83], v[76:79], v[34:37]
	ds_read_b128 v[80:83], v71 offset:35008
	v_mfma_f32_16x16x32_bf16 v[46:49], v[84:87], v[76:79], v[46:49]
	ds_read_b128 v[84:87], v71 offset:39360
	ds_read_b128 v[76:79], v88 offset:192
	s_waitcnt lgkmcnt(0)
	v_mfma_f32_16x16x32_bf16 v[42:45], v[80:83], v[76:79], v[42:45]
	v_mfma_f32_16x16x32_bf16 v[38:41], v[84:87], v[76:79], v[38:41]
	ds_read_b128 v[76:79], v88 offset:4544
	s_nop 5
	v_pk_add_f32 v[42:43], v[70:71], v[42:43] op_sel_hi:[0,1]
	v_pk_add_f32 v[44:45], v[70:71], v[44:45] op_sel_hi:[0,1]
	s_waitcnt lgkmcnt(0)
	v_mfma_f32_16x16x32_bf16 v[54:57], v[80:83], v[76:79], v[54:57]
	v_add_f32_e64 v38, v70, v38
	v_add_f32_e64 v39, v70, v39
	v_mfma_f32_16x16x32_bf16 v[50:53], v[84:87], v[76:79], v[50:53]
	ds_read_b128 v[76:79], v88 offset:8896
	v_pk_add_f32 v[40:41], v[70:71], v[40:41] op_sel_hi:[0,1]
	v_permlane16_swap_b32_e32 v42, v38
	v_permlane16_swap_b32_e32 v43, v39
	v_lshlrev_b32_e32 v70, 16, v30
	v_and_b32_e32 v30, 0xffff0000, v30
	v_mul_f32_e32 v42, v70, v42
	v_lshlrev_b32_e32 v70, 16, v26
	v_mul_f32_e32 v30, v30, v43
	v_and_b32_e32 v26, 0xffff0000, v26
	v_permlane16_swap_b32_e32 v44, v40
	v_permlane16_swap_b32_e32 v45, v41
	v_mul_f32_e32 v42, v42, v70
	v_mul_f32_e32 v26, v30, v26
	v_lshlrev_b32_e32 v30, 16, v31
	v_and_b32_e32 v31, 0xffff0000, v31
	s_waitcnt lgkmcnt(0)
	v_mfma_f32_16x16x32_bf16 v[72:75], v[80:83], v[76:79], v[72:75]
	v_mul_f32_e32 v30, v30, v44
	v_mul_f32_e32 v31, v31, v45
	v_mfma_f32_16x16x32_bf16 v[58:61], v[84:87], v[76:79], v[58:61]
	ds_read_b128 v[76:79], v88 offset:13248
	v_cvt_pk_bf16_f32 v26, v42, v26
	v_lshlrev_b32_e32 v42, 16, v27
	v_and_b32_e32 v27, 0xffff0000, v27
	v_mul_f32_e32 v30, v30, v42
	v_mul_f32_e32 v27, v31, v27
	v_cvt_pk_bf16_f32 v27, v30, v27
	v_lshlrev_b32_e32 v30, 16, v32
	v_mul_f32_e32 v30, v30, v38
	v_lshlrev_b32_e32 v31, 16, v28
	v_mul_f32_e32 v30, v30, v31
	v_and_b32_e32 v31, 0xffff0000, v32
	v_mul_f32_e32 v31, v31, v39
	v_and_b32_e32 v28, 0xffff0000, v28
	v_mul_f32_e32 v28, v31, v28
	v_cvt_pk_bf16_f32 v28, v30, v28
	v_lshlrev_b32_e32 v30, 16, v33
	v_mul_f32_e32 v30, v30, v40
	v_lshlrev_b32_e32 v31, 16, v29
	v_mul_f32_e32 v30, v30, v31
	v_and_b32_e32 v31, 0xffff0000, v33
	v_mul_f32_e32 v31, v31, v41
	v_and_b32_e32 v29, 0xffff0000, v29
	v_mul_f32_e32 v29, v31, v29
	v_cvt_pk_bf16_f32 v29, v30, v29
	global_store_dwordx4 v[66:67], v[26:29], off offset:2048 sc1
	v_pk_add_f32 v[32:33], v[68:69], v[50:51] op_sel_hi:[0,1]
	v_lshlrev_b32_e32 v38, 16, v22
	v_pk_add_f32 v[28:29], v[68:69], v[54:55] op_sel_hi:[0,1]
	s_nop 1
	v_permlane16_swap_b32_e32 v28, v32
	v_permlane16_swap_b32_e32 v29, v33
	v_and_b32_e32 v22, 0xffff0000, v22
	v_pk_add_f32 v[26:27], v[68:69], v[56:57] op_sel_hi:[0,1]
	v_pk_add_f32 v[30:31], v[68:69], v[52:53] op_sel_hi:[0,1]
	v_mul_f32_e32 v28, v38, v28
	v_lshlrev_b32_e32 v38, 16, v18
	v_mul_f32_e32 v22, v22, v29
	v_and_b32_e32 v18, 0xffff0000, v18
	v_permlane16_swap_b32_e32 v26, v30
	v_permlane16_swap_b32_e32 v27, v31
	v_mul_f32_e32 v18, v22, v18
	v_lshlrev_b32_e32 v22, 16, v23
	v_and_b32_e32 v23, 0xffff0000, v23
	v_mul_f32_e32 v22, v22, v26
	v_lshlrev_b32_e32 v26, 16, v19
	v_mul_f32_e32 v23, v23, v27
	v_and_b32_e32 v19, 0xffff0000, v19
	v_mul_f32_e32 v22, v22, v26
	v_mul_f32_e32 v19, v23, v19
	v_mul_f32_e32 v28, v28, v38
	v_cvt_pk_bf16_f32 v18, v28, v18
	v_cvt_pk_bf16_f32 v19, v22, v19
	v_lshlrev_b32_e32 v22, 16, v24
	v_mul_f32_e32 v22, v22, v32
	v_lshlrev_b32_e32 v23, 16, v20
	v_mul_f32_e32 v22, v22, v23
	v_and_b32_e32 v23, 0xffff0000, v24
	v_mul_f32_e32 v23, v23, v33
	v_and_b32_e32 v20, 0xffff0000, v20
	v_mul_f32_e32 v20, v23, v20
	v_cvt_pk_bf16_f32 v20, v22, v20
	v_lshlrev_b32_e32 v22, 16, v25
	v_mul_f32_e32 v22, v22, v30
	v_lshlrev_b32_e32 v23, 16, v21
	v_mul_f32_e32 v22, v22, v23
	v_and_b32_e32 v23, 0xffff0000, v25
	v_mul_f32_e32 v23, v23, v31
	v_and_b32_e32 v21, 0xffff0000, v21
	v_mul_f32_e32 v21, v23, v21
	v_cvt_pk_bf16_f32 v21, v22, v21
	v_mov_b64_e32 v[22:23], s[28:29]
	v_mad_i64_i32 v[24:25], s[38:39], v69, s23, v[22:23]
	v_lshl_add_u64 v[24:25], v[24:25], 0, s[30:31]
	v_lshl_add_u64 v[24:25], v[24:25], 0, v[0:1]
	global_store_dwordx4 v[24:25], v[18:21], off offset:2048 sc1
	v_pk_add_f32 v[26:27], v[64:65], v[58:59] op_sel_hi:[0,1]
	v_lshlrev_b32_e32 v28, 16, v14
	v_pk_add_f32 v[20:21], v[64:65], v[72:73] op_sel_hi:[0,1]
	s_nop 1
	v_permlane16_swap_b32_e32 v20, v26
	v_permlane16_swap_b32_e32 v21, v27
	v_and_b32_e32 v14, 0xffff0000, v14
	v_pk_add_f32 v[18:19], v[64:65], v[74:75] op_sel_hi:[0,1]
	v_pk_add_f32 v[24:25], v[64:65], v[60:61] op_sel_hi:[0,1]
	v_mul_f32_e32 v20, v28, v20
	v_lshlrev_b32_e32 v28, 16, v10
	v_mul_f32_e32 v14, v14, v21
	v_and_b32_e32 v10, 0xffff0000, v10
	v_permlane16_swap_b32_e32 v18, v24
	v_permlane16_swap_b32_e32 v19, v25
	v_mul_f32_e32 v10, v14, v10
	v_lshlrev_b32_e32 v14, 16, v15
	v_and_b32_e32 v15, 0xffff0000, v15
	v_mul_f32_e32 v14, v14, v18
	v_lshlrev_b32_e32 v18, 16, v11
	v_mul_f32_e32 v15, v15, v19
	v_and_b32_e32 v11, 0xffff0000, v11
	v_mul_f32_e32 v14, v14, v18
	v_mul_f32_e32 v11, v15, v11
	v_mul_f32_e32 v20, v20, v28
	v_cvt_pk_bf16_f32 v10, v20, v10
	v_cvt_pk_bf16_f32 v11, v14, v11
	v_lshlrev_b32_e32 v14, 16, v16
	v_mul_f32_e32 v14, v14, v26
	v_lshlrev_b32_e32 v15, 16, v12
	v_mul_f32_e32 v14, v14, v15
	v_and_b32_e32 v15, 0xffff0000, v16
	v_mul_f32_e32 v15, v15, v27
	v_and_b32_e32 v12, 0xffff0000, v12
	v_mul_f32_e32 v12, v15, v12
	v_cvt_pk_bf16_f32 v12, v14, v12
	v_lshlrev_b32_e32 v14, 16, v17
	v_mul_f32_e32 v14, v14, v24
	v_lshlrev_b32_e32 v15, 16, v13
	v_mul_f32_e32 v14, v14, v15
	v_and_b32_e32 v15, 0xffff0000, v17
	v_mul_f32_e32 v15, v15, v25
	v_and_b32_e32 v13, 0xffff0000, v13
	s_waitcnt lgkmcnt(0)
	v_mfma_f32_16x16x32_bf16 v[34:37], v[80:83], v[76:79], v[34:37]
	v_mul_f32_e32 v13, v15, v13
	v_cvt_pk_bf16_f32 v13, v14, v13
	v_mad_i64_i32 v[14:15], s[38:39], v65, s23, v[22:23]
	v_mfma_f32_16x16x32_bf16 v[46:49], v[84:87], v[76:79], v[46:49]
	v_lshl_add_u64 v[14:15], v[14:15], 0, s[30:31]
	v_lshl_add_u64 v[14:15], v[14:15], 0, v[0:1]
	global_store_dwordx4 v[14:15], v[10:13], off offset:2048 sc1
	v_lshlrev_b32_e32 v18, 16, v6
	v_and_b32_e32 v6, 0xffff0000, v6
	v_pk_add_f32 v[12:13], v[62:63], v[34:35] op_sel_hi:[0,1]
	s_nop 1
	v_pk_add_f32 v[16:17], v[62:63], v[46:47] op_sel_hi:[0,1]
	s_nop 1
	v_permlane16_swap_b32_e32 v12, v16
	v_permlane16_swap_b32_e32 v13, v17
	v_pk_add_f32 v[10:11], v[62:63], v[36:37] op_sel_hi:[0,1]
	v_pk_add_f32 v[14:15], v[62:63], v[48:49] op_sel_hi:[0,1]
	v_mul_f32_e32 v12, v18, v12
	v_lshlrev_b32_e32 v18, 16, v2
	v_mul_f32_e32 v6, v6, v13
	v_and_b32_e32 v2, 0xffff0000, v2
	v_permlane16_swap_b32_e32 v10, v14
	v_permlane16_swap_b32_e32 v11, v15
	v_mul_f32_e32 v2, v6, v2
	v_lshlrev_b32_e32 v6, 16, v7
	v_and_b32_e32 v7, 0xffff0000, v7
	v_mul_f32_e32 v6, v6, v10
	v_lshlrev_b32_e32 v10, 16, v3
	v_mul_f32_e32 v7, v7, v11
	v_and_b32_e32 v3, 0xffff0000, v3
	v_mul_f32_e32 v6, v6, v10
	v_mul_f32_e32 v3, v7, v3
	v_mul_f32_e32 v12, v12, v18
	v_cvt_pk_bf16_f32 v2, v12, v2
	v_cvt_pk_bf16_f32 v3, v6, v3
	v_lshlrev_b32_e32 v6, 16, v8
	v_mul_f32_e32 v6, v6, v16
	v_lshlrev_b32_e32 v7, 16, v4
	v_mul_f32_e32 v6, v6, v7
	v_and_b32_e32 v7, 0xffff0000, v8
	v_mul_f32_e32 v7, v7, v17
	v_and_b32_e32 v4, 0xffff0000, v4
	v_mul_f32_e32 v4, v7, v4
	v_cvt_pk_bf16_f32 v4, v6, v4
	v_lshlrev_b32_e32 v6, 16, v9
	v_mul_f32_e32 v6, v6, v14
	v_lshlrev_b32_e32 v7, 16, v5
	v_mul_f32_e32 v6, v6, v7
	v_and_b32_e32 v7, 0xffff0000, v9
	v_mul_f32_e32 v7, v7, v15
	v_and_b32_e32 v5, 0xffff0000, v5
	v_mul_f32_e32 v5, v7, v5
	v_cvt_pk_bf16_f32 v5, v6, v5
	v_mad_i64_i32 v[6:7], s[38:39], v63, s23, v[22:23]
	v_lshl_add_u64 v[6:7], v[6:7], 0, s[30:31]
	v_lshl_add_u64 v[6:7], v[6:7], 0, v[0:1]
	global_store_dwordx4 v[6:7], v[2:5], off offset:2048 sc1
	s_barrier
	s_branch .LBB0_443
